# instruction selection: packed f32 adds of the FoX / compressed / window softmax row-sum chains split into scalar add pairs
# speedup vs baseline: 1.0111x; 1.0111x over previous
.LBB0_798:
	v_exp_f32_e32 v2, v68
	v_exp_f32_e32 v3, v69
	v_exp_f32_e32 v52, v52
	v_exp_f32_e32 v53, v53
	v_exp_f32_e32 v70, v70
	v_exp_f32_e32 v71, v71
	v_exp_f32_e32 v54, v54
	v_exp_f32_e32 v55, v55
	v_add_f32_e32 v68, 0, v2
	v_add_f32_e32 v69, 0, v3
	v_exp_f32_e32 v72, v72
	v_exp_f32_e32 v73, v73
	v_add_f32_e32 v68, v52, v68
	v_add_f32_e32 v69, v53, v69
	v_exp_f32_e32 v56, v56
	v_exp_f32_e32 v57, v57
	v_add_f32_e32 v68, v70, v68
	v_add_f32_e32 v69, v71, v69
	v_exp_f32_e32 v74, v74
	v_exp_f32_e32 v75, v75
	v_add_f32_e32 v68, v54, v68
	v_add_f32_e32 v69, v55, v69
	v_exp_f32_e32 v58, v58
	v_exp_f32_e32 v59, v59
	v_add_f32_e32 v68, v72, v68
	v_add_f32_e32 v69, v73, v69
	v_exp_f32_e32 v76, v76
	v_exp_f32_e32 v77, v77
	v_add_f32_e32 v68, v56, v68
	v_add_f32_e32 v69, v57, v69
	v_exp_f32_e32 v60, v60
	v_exp_f32_e32 v61, v61
	v_add_f32_e32 v68, v74, v68
	v_add_f32_e32 v69, v75, v69
	v_exp_f32_e32 v78, v78
	v_exp_f32_e32 v79, v79
	v_add_f32_e32 v68, v58, v68
	v_add_f32_e32 v69, v59, v69
	v_exp_f32_e32 v62, v62
	v_exp_f32_e32 v63, v63
	v_add_f32_e32 v68, v76, v68
	v_add_f32_e32 v69, v77, v69
	v_exp_f32_e32 v80, v80
	v_exp_f32_e32 v81, v81
	v_add_f32_e32 v68, v60, v68
	v_add_f32_e32 v69, v61, v69
	v_exp_f32_e32 v64, v64
	v_exp_f32_e32 v65, v65
	v_add_f32_e32 v68, v78, v68
	v_add_f32_e32 v69, v79, v69
	v_exp_f32_e32 v82, v82
	v_exp_f32_e32 v83, v83
	v_add_f32_e32 v68, v62, v68
	v_add_f32_e32 v69, v63, v69
	v_exp_f32_e32 v66, v66
	v_exp_f32_e32 v67, v67
	v_add_f32_e32 v68, v80, v68
	v_add_f32_e32 v69, v81, v69
	v_cvt_pk_bf16_f32 v88, v60, v61
	v_add_f32_e32 v68, v64, v68
	v_add_f32_e32 v69, v65, v69
	v_cvt_pk_bf16_f32 v89, v62, v63
	v_add_f32_e32 v68, v82, v68
	v_add_f32_e32 v69, v83, v69
	s_add_i32 s8, s17, 1
	v_add_f32_e32 v68, v66, v68
	v_add_f32_e32 v69, v67, v69
	s_cmp_lg_u32 s8, 3
	v_pk_add_f32 v[84:85], v[68:69], v[68:69] op_sel:[0,1] op_sel_hi:[1,0]
	v_cvt_pk_bf16_f32 v69, v70, v71
	v_cvt_pk_bf16_f32 v70, v72, v73
	v_cvt_pk_bf16_f32 v71, v74, v75
	v_cvt_pk_bf16_f32 v72, v76, v77
	v_cvt_pk_bf16_f32 v73, v78, v79
	v_cvt_pk_bf16_f32 v74, v80, v81
	v_cvt_pk_bf16_f32 v75, v82, v83
	v_cvt_pk_bf16_f32 v76, v52, v53
	v_cvt_pk_bf16_f32 v77, v54, v55
	v_cvt_pk_bf16_f32 v78, v56, v57
	v_cvt_pk_bf16_f32 v79, v58, v59
	ds_read_b128 v[52:55], v0 offset:9216
	ds_read_b128 v[56:59], v0 offset:9248
	ds_read_b128 v[60:63], v0 offset:9280
	ds_read_b128 v[80:83], v0 offset:9312
	s_cselect_b32 s22, s8, 0
	s_add_i32 s8, s22, 1
	s_cmp_lg_u32 s8, 3
	v_mov_b32_e32 v85, v84
	s_cselect_b32 s17, s8, 0
	s_nop 0
	v_permlane32_swap_b32_e32 v84, v85
	v_cvt_pk_bf16_f32 v68, v2, v3
	v_cvt_pk_bf16_f32 v90, v64, v65
	v_cvt_pk_bf16_f32 v91, v66, v67
	s_waitcnt lgkmcnt(3)
	v_mfma_f32_32x32x16_bf16 v[36:51], v[52:55], v[68:71], v[36:51]
	s_waitcnt lgkmcnt(2)
	v_mfma_f32_32x32x16_bf16 v[36:51], v[56:59], v[72:75], v[36:51]
	s_waitcnt lgkmcnt(1)
	v_mfma_f32_32x32x16_bf16 v[36:51], v[60:63], v[76:79], v[36:51]
	s_waitcnt lgkmcnt(0)
	v_mfma_f32_32x32x16_bf16 v[36:51], v[80:83], v[88:91], v[36:51]
	ds_read_b128 v[52:55], v0 offset:13824
	ds_read_b128 v[56:59], v0 offset:13856
	ds_read_b128 v[60:63], v0 offset:13888
	ds_read_b128 v[64:67], v0 offset:13920
	s_waitcnt lgkmcnt(3)
	v_mfma_f32_32x32x16_bf16 v[20:35], v[52:55], v[68:71], v[20:35]
	s_waitcnt lgkmcnt(2)
	v_mfma_f32_32x32x16_bf16 v[20:35], v[56:59], v[72:75], v[20:35]
	s_waitcnt lgkmcnt(1)
	v_mfma_f32_32x32x16_bf16 v[20:35], v[60:63], v[76:79], v[20:35]
	s_waitcnt lgkmcnt(0)
	v_mfma_f32_32x32x16_bf16 v[20:35], v[64:67], v[88:91], v[20:35]
	s_add_i32 s21, s13, -2
	s_cmp_ge_i32 s21, s12
	s_cbranch_scc1 .LBB0_802
	s_mul_i32 s8, s17, 0x4900
	s_add_i32 s10, s33, s8
	v_add3_u32 v0, s10, v171, v166
	s_waitcnt vmcnt(1)
	ds_write_b128 v0, v[132:135]
	s_waitcnt vmcnt(0)
	ds_write_b128 v0, v[136:139] offset:9216
	s_and_saveexec_b64 s[8:9], s[6:7]
	s_cbranch_execz .LBB0_801
	v_add_f32_e32 v170, v170, v223
	v_sub_f32_e32 v170, v155, v170
	v_cvt_pk_bf16_f32 v0, v170, 0
	v_and_b32_e32 v2, 0xffff, v0
	v_lshlrev_b32_e32 v0, 16, v0
	v_sub_f32_e32 v0, v170, v0
	v_cvt_pk_bf16_f32 v0, v0, 0
	v_lshl_or_b32 v0, v0, 16, v2
	v_mov_b32_e32 v2, v1
	v_mov_b32_e32 v3, v1
	v_add_u32_e32 v52, s10, v172
	ds_write_b128 v52, v[0:3] offset:128

.LBB0_812:
	v_exp_f32_e32 v2, v100
	v_exp_f32_e32 v3, v101
	v_exp_f32_e32 v100, v84
	v_exp_f32_e32 v101, v85
	v_exp_f32_e32 v102, v102
	v_exp_f32_e32 v103, v103
	v_exp_f32_e32 v178, v86
	v_exp_f32_e32 v179, v87
	v_add_f32_e32 v84, 0, v2
	v_add_f32_e32 v85, 0, v3
	v_exp_f32_e32 v104, v104
	v_exp_f32_e32 v105, v105
	v_add_f32_e32 v84, v100, v84
	v_add_f32_e32 v85, v101, v85
	v_exp_f32_e32 v204, v88
	v_exp_f32_e32 v205, v89
	v_add_f32_e32 v84, v102, v84
	v_add_f32_e32 v85, v103, v85
	v_exp_f32_e32 v106, v106
	v_exp_f32_e32 v107, v107
	v_add_f32_e32 v84, v178, v84
	v_add_f32_e32 v85, v179, v85
	v_exp_f32_e32 v206, v90
	v_exp_f32_e32 v207, v91
	v_add_f32_e32 v84, v104, v84
	v_add_f32_e32 v85, v105, v85
	v_exp_f32_e32 v90, v108
	v_exp_f32_e32 v91, v109
	v_add_f32_e32 v84, v204, v84
	v_add_f32_e32 v85, v205, v85
	v_exp_f32_e32 v108, v92
	v_exp_f32_e32 v109, v93
	v_add_f32_e32 v84, v106, v84
	v_add_f32_e32 v85, v107, v85
	v_exp_f32_e32 v92, v110
	v_exp_f32_e32 v93, v111
	v_add_f32_e32 v84, v206, v84
	v_add_f32_e32 v85, v207, v85
	v_exp_f32_e32 v110, v94
	v_exp_f32_e32 v111, v95
	v_add_f32_e32 v84, v90, v84
	v_add_f32_e32 v85, v91, v85
	v_exp_f32_e32 v94, v112
	v_exp_f32_e32 v95, v113
	v_add_f32_e32 v84, v108, v84
	v_add_f32_e32 v85, v109, v85
	v_exp_f32_e32 v112, v96
	v_exp_f32_e32 v113, v97
	v_add_f32_e32 v84, v92, v84
	v_add_f32_e32 v85, v93, v85
	v_exp_f32_e32 v96, v114
	v_exp_f32_e32 v97, v115
	v_add_f32_e32 v84, v110, v84
	v_add_f32_e32 v85, v111, v85
	v_exp_f32_e32 v114, v98
	v_add_f32_e32 v84, v94, v84
	v_add_f32_e32 v85, v95, v85
	v_exp_f32_e32 v115, v99
	v_add_f32_e32 v84, v112, v84
	v_add_f32_e32 v85, v113, v85
	v_cvt_pk_bf16_f32 v87, v102, v103
	v_add_f32_e32 v84, v96, v84
	v_add_f32_e32 v85, v97, v85
	v_cvt_pk_bf16_f32 v88, v104, v105
	v_cvt_pk_bf16_f32 v89, v106, v107
	v_cvt_pk_bf16_f32 v90, v90, v91
	v_cvt_pk_bf16_f32 v91, v92, v93
	v_cvt_pk_bf16_f32 v92, v94, v95
	v_cvt_pk_bf16_f32 v93, v96, v97
	v_cvt_pk_bf16_f32 v94, v100, v101
	v_cvt_pk_bf16_f32 v96, v204, v205
	v_cvt_pk_bf16_f32 v97, v206, v207
	v_cvt_pk_bf16_f32 v98, v108, v109
	v_cvt_pk_bf16_f32 v99, v110, v111
	v_cvt_pk_bf16_f32 v100, v112, v113
	ds_read_b128 v[102:105], v0 offset:9216
	ds_read_b128 v[106:109], v0 offset:9248
	ds_read_b128 v[110:113], v0 offset:9280
	ds_read_b128 v[204:207], v0 offset:9312
	v_add_f32_e32 v84, v114, v84
	v_add_f32_e32 v85, v115, v85
	v_cvt_pk_bf16_f32 v86, v2, v3
	v_pk_add_f32 v[84:85], v[84:85], v[84:85] op_sel:[0,1] op_sel_hi:[1,0]
	v_cvt_pk_bf16_f32 v95, v178, v179
	v_mov_b32_e32 v85, v84
	s_nop 1
	v_permlane32_swap_b32_e32 v84, v85
	v_cvt_pk_bf16_f32 v101, v114, v115
	s_waitcnt lgkmcnt(3)
	v_mfma_f32_32x32x16_bf16 v[36:51], v[102:105], v[86:89], v[36:51]
	s_waitcnt lgkmcnt(2)
	v_mfma_f32_32x32x16_bf16 v[36:51], v[106:109], v[90:93], v[36:51]
	s_waitcnt lgkmcnt(1)
	v_mfma_f32_32x32x16_bf16 v[36:51], v[110:113], v[94:97], v[36:51]
	s_waitcnt lgkmcnt(0)
	v_mfma_f32_32x32x16_bf16 v[36:51], v[204:207], v[98:101], v[36:51]
	ds_read_b128 v[102:105], v0 offset:13824
	ds_read_b128 v[106:109], v0 offset:13856
	ds_read_b128 v[110:113], v0 offset:13888
	ds_read_b128 v[204:207], v0 offset:13920
	s_waitcnt lgkmcnt(3)
	v_mfma_f32_32x32x16_bf16 v[20:35], v[102:105], v[86:89], v[20:35]
	s_waitcnt lgkmcnt(2)
	v_mfma_f32_32x32x16_bf16 v[20:35], v[106:109], v[90:93], v[20:35]
	s_waitcnt lgkmcnt(1)
	v_mfma_f32_32x32x16_bf16 v[20:35], v[110:113], v[94:97], v[20:35]
	s_waitcnt lgkmcnt(0)
	v_mfma_f32_32x32x16_bf16 v[20:35], v[204:207], v[98:101], v[20:35]
	s_andn2_b64 vcc, exec, s[0:1]
	s_cbranch_vccnz .LBB0_788
	v_add3_u32 v0, s20, v171, v166
	s_waitcnt vmcnt(1)
	ds_write_b128 v0, v[140:143]
	s_waitcnt vmcnt(0)
	ds_write_b128 v0, v[144:147] offset:9216
	s_and_saveexec_b64 s[0:1], s[6:7]
	s_cbranch_execz .LBB0_787
	v_add_f32_e32 v167, v167, v222
	v_sub_f32_e32 v167, v155, v167
	v_cvt_pk_bf16_f32 v0, v167, 0
	v_and_b32_e32 v2, 0xffff, v0
	v_lshlrev_b32_e32 v0, 16, v0
	v_sub_f32_e32 v0, v167, v0
	v_cvt_pk_bf16_f32 v0, v0, 0
	v_lshl_or_b32 v0, v0, 16, v2
	v_mov_b32_e32 v2, v1
	v_mov_b32_e32 v3, v1
	v_add_u32_e32 v86, s20, v172
	ds_write_b128 v86, v[0:3] offset:128
	s_branch .LBB0_787

.LBB0_845:
	v_exp_f32_e32 v34, v34
	v_exp_f32_e32 v35, v35
	v_exp_f32_e32 v18, v18
	v_exp_f32_e32 v19, v19
	v_exp_f32_e32 v20, v20
	v_add_f32_e32 v34, 0, v34
	v_add_f32_e32 v35, 0, v35
	v_exp_f32_e32 v21, v21
	v_add_f32_e32 v18, v18, v34
	v_add_f32_e32 v19, v19, v35
	v_exp_f32_e32 v34, v36
	v_exp_f32_e32 v35, v37
	v_exp_f32_e32 v22, v22
	v_exp_f32_e32 v23, v23
	s_add_i32 s14, s19, 1
	v_add_f32_e32 v18, v34, v18
	v_add_f32_e32 v19, v35, v19
	s_cmp_lg_u32 s14, 3
	v_add_f32_e32 v18, v20, v18
	v_add_f32_e32 v19, v21, v19
	v_exp_f32_e32 v20, v38
	v_exp_f32_e32 v21, v39
	s_cselect_b32 s24, s14, 0
	s_add_i32 s14, s24, 1
	s_cmp_lg_u32 s14, 3
	v_add_f32_e32 v18, v20, v18
	v_add_f32_e32 v19, v21, v19
	v_exp_f32_e32 v20, v40
	v_exp_f32_e32 v21, v41
	v_add_f32_e32 v18, v22, v18
	v_add_f32_e32 v19, v23, v19
	v_exp_f32_e32 v22, v24
	v_exp_f32_e32 v23, v25
	v_add_f32_e32 v18, v20, v18
	v_add_f32_e32 v19, v21, v19
	v_exp_f32_e32 v20, v42
	v_exp_f32_e32 v21, v43
	v_add_f32_e32 v18, v22, v18
	v_add_f32_e32 v19, v23, v19
	v_exp_f32_e32 v22, v26
	v_exp_f32_e32 v23, v27
	v_add_f32_e32 v18, v20, v18
	v_add_f32_e32 v19, v21, v19
	v_exp_f32_e32 v20, v44
	v_exp_f32_e32 v21, v45
	v_add_f32_e32 v18, v22, v18
	v_add_f32_e32 v19, v23, v19
	v_exp_f32_e32 v22, v28
	v_exp_f32_e32 v23, v29
	v_add_f32_e32 v18, v20, v18
	v_add_f32_e32 v19, v21, v19
	v_exp_f32_e32 v20, v46
	v_exp_f32_e32 v21, v47
	v_add_f32_e32 v18, v22, v18
	v_add_f32_e32 v19, v23, v19
	v_exp_f32_e32 v22, v30
	v_exp_f32_e32 v23, v31
	v_add_f32_e32 v18, v20, v18
	v_add_f32_e32 v19, v21, v19
	v_exp_f32_e32 v20, v48
	v_exp_f32_e32 v21, v49
	v_add_f32_e32 v18, v22, v18
	v_add_f32_e32 v19, v23, v19
	v_exp_f32_e32 v22, v32
	v_exp_f32_e32 v23, v33
	v_add_f32_e32 v18, v20, v18
	v_add_f32_e32 v19, v21, v19
	s_cselect_b32 s19, s14, 0
	s_add_i32 s23, s20, -2
	v_add_f32_e32 v18, v22, v18
	v_add_f32_e32 v19, v23, v19
	s_cmp_ge_i32 s23, s17
	v_pk_add_f32 v[18:19], v[18:19], v[18:19] op_sel:[0,1] op_sel_hi:[1,0]
	s_nop 0
	v_mov_b32_e32 v0, v18
	s_nop 1
	v_permlane32_swap_b32_e32 v18, v0
	s_cbranch_scc1 .LBB0_847
	s_mul_i32 s14, s19, 0x4900
	v_add_u32_e32 v19, s14, v101
	s_waitcnt vmcnt(0)
	ds_write_b128 v19, v[50:53]

.LBB0_854:
	v_exp_f32_e32 v34, v34
	v_exp_f32_e32 v35, v35
	v_exp_f32_e32 v18, v18
	v_exp_f32_e32 v19, v19
	v_exp_f32_e32 v20, v20
	v_add_f32_e32 v34, 0, v34
	v_add_f32_e32 v35, 0, v35
	v_exp_f32_e32 v21, v21
	v_add_f32_e32 v18, v18, v34
	v_add_f32_e32 v19, v19, v35
	v_exp_f32_e32 v34, v36
	v_exp_f32_e32 v35, v37
	v_exp_f32_e32 v22, v22
	v_exp_f32_e32 v23, v23
	s_andn2_b64 vcc, exec, s[12:13]
	v_add_f32_e32 v18, v34, v18
	v_add_f32_e32 v19, v35, v19
	s_nop 0
	v_add_f32_e32 v18, v20, v18
	v_add_f32_e32 v19, v21, v19
	v_exp_f32_e32 v20, v38
	v_exp_f32_e32 v21, v39
	s_nop 0
	v_add_f32_e32 v18, v20, v18
	v_add_f32_e32 v19, v21, v19
	v_exp_f32_e32 v20, v40
	v_exp_f32_e32 v21, v41
	v_add_f32_e32 v18, v22, v18
	v_add_f32_e32 v19, v23, v19
	v_exp_f32_e32 v22, v24
	v_exp_f32_e32 v23, v25
	v_add_f32_e32 v18, v20, v18
	v_add_f32_e32 v19, v21, v19
	v_exp_f32_e32 v20, v42
	v_exp_f32_e32 v21, v43
	v_add_f32_e32 v18, v22, v18
	v_add_f32_e32 v19, v23, v19
	v_exp_f32_e32 v22, v26
	v_exp_f32_e32 v23, v27
	v_add_f32_e32 v18, v20, v18
	v_add_f32_e32 v19, v21, v19
	v_exp_f32_e32 v20, v44
	v_exp_f32_e32 v21, v45
	v_add_f32_e32 v18, v22, v18
	v_add_f32_e32 v19, v23, v19
	v_exp_f32_e32 v22, v28
	v_exp_f32_e32 v23, v29
	v_add_f32_e32 v18, v20, v18
	v_add_f32_e32 v19, v21, v19
	v_exp_f32_e32 v20, v46
	v_exp_f32_e32 v21, v47
	v_add_f32_e32 v18, v22, v18
	v_add_f32_e32 v19, v23, v19
	v_exp_f32_e32 v22, v30
	v_exp_f32_e32 v23, v31
	v_add_f32_e32 v18, v20, v18
	v_add_f32_e32 v19, v21, v19
	v_exp_f32_e32 v20, v48
	v_exp_f32_e32 v21, v49
	v_add_f32_e32 v18, v22, v18
	v_add_f32_e32 v19, v23, v19
	v_exp_f32_e32 v22, v32
	v_exp_f32_e32 v23, v33
	v_add_f32_e32 v18, v20, v18
	v_add_f32_e32 v19, v21, v19
	s_nop 0
	v_add_f32_e32 v18, v22, v18
	v_add_f32_e32 v19, v23, v19
	s_nop 0
	v_pk_add_f32 v[18:19], v[18:19], v[18:19] op_sel:[0,1] op_sel_hi:[1,0]
	s_nop 0
	v_mov_b32_e32 v0, v18
	s_nop 1
	v_permlane32_swap_b32_e32 v18, v0
	s_cbranch_vccnz .LBB0_838
	v_add3_u32 v19, s22, v207, v102
	s_waitcnt vmcnt(0)
	ds_write_b128 v19, v[54:57]
	s_branch .LBB0_838

.LBB0_866:
	s_nop 6
	v_exp_f32_e32 v66, v66
	v_exp_f32_e32 v67, v67
	v_exp_f32_e32 v68, v68
	v_exp_f32_e32 v69, v69
	v_exp_f32_e32 v70, v70
	v_pk_mul_f32 v[66:67], v[120:121], v[66:67]
	v_exp_f32_e32 v71, v71
	v_pk_mul_f32 v[68:69], v[120:121], v[68:69]
	v_add_f32_e32 v124, v66, v67
	v_fma_f32 v126, 0.5, v69, v68
	v_exp_f32_e32 v72, v72
	v_exp_f32_e32 v73, v73
	v_add_f32_e32 v124, v124, v126
	v_mul_f32_e32 v125, 0.5, v69
	v_pk_mul_f32 v[70:71], v[120:121], v[70:71]
	v_add_f32_dpp v124, v124, v124 quad_perm:[1,0,3,2] row_mask:0xf bank_mask:0xf bound_ctrl:1
	v_pk_mul_f32 v[72:73], v[120:121], v[72:73]
	v_exp_f32_e32 v74, v74
	v_add_f32_dpp v158, v124, v124 quad_perm:[2,3,0,1] row_mask:0xf bank_mask:0xf bound_ctrl:1
	v_mov_b32_e32 v124, 0
	v_fma_f32 v126, 0.5, v73, v72
	v_exp_f32_e32 v75, v75
	v_mov_b32_dpp v124, v125 quad_perm:[1,0,3,2] row_mask:0xf bank_mask:0xf
	v_fmac_f32_e32 v124, 0.5, v69
	v_exp_f32_e32 v76, v76
	v_exp_f32_e32 v77, v77
	v_add_f32_dpp v159, v124, v124 quad_perm:[2,3,0,1] row_mask:0xf bank_mask:0xf bound_ctrl:1
	v_add_f32_e32 v124, v70, v71
	v_add_f32_e32 v124, v124, v126
	v_mul_f32_e32 v125, 0.5, v73
	v_pk_mul_f32 v[74:75], v[120:121], v[74:75]
	v_add_f32_dpp v124, v124, v124 quad_perm:[1,0,3,2] row_mask:0xf bank_mask:0xf bound_ctrl:1
	v_pk_mul_f32 v[76:77], v[120:121], v[76:77]
	v_exp_f32_e32 v78, v78
	v_add_f32_dpp v170, v124, v124 quad_perm:[2,3,0,1] row_mask:0xf bank_mask:0xf bound_ctrl:1
	v_mov_b32_e32 v124, 0
	v_fma_f32 v126, 0.5, v77, v76
	v_exp_f32_e32 v79, v79
	v_mov_b32_dpp v124, v125 quad_perm:[1,0,3,2] row_mask:0xf bank_mask:0xf
	v_fmac_f32_e32 v124, 0.5, v73
	v_exp_f32_e32 v80, v80
	v_exp_f32_e32 v81, v81
	v_add_f32_dpp v171, v124, v124 quad_perm:[2,3,0,1] row_mask:0xf bank_mask:0xf bound_ctrl:1
	v_add_f32_e32 v124, v74, v75
	v_add_f32_e32 v124, v124, v126
	v_mul_f32_e32 v125, 0.5, v77
	v_pk_mul_f32 v[78:79], v[120:121], v[78:79]
	v_add_f32_dpp v124, v124, v124 quad_perm:[1,0,3,2] row_mask:0xf bank_mask:0xf bound_ctrl:1
	v_pk_mul_f32 v[80:81], v[120:121], v[80:81]
	v_exp_f32_e32 v50, v50
	v_add_f32_dpp v156, v124, v124 quad_perm:[2,3,0,1] row_mask:0xf bank_mask:0xf bound_ctrl:1
	v_mov_b32_e32 v124, 0
	v_fma_f32 v126, 0.5, v81, v80
	v_exp_f32_e32 v51, v51
	v_mov_b32_dpp v124, v125 quad_perm:[1,0,3,2] row_mask:0xf bank_mask:0xf
	v_fmac_f32_e32 v124, 0.5, v77
	v_exp_f32_e32 v52, v52
	v_exp_f32_e32 v53, v53
	v_add_f32_dpp v157, v124, v124 quad_perm:[2,3,0,1] row_mask:0xf bank_mask:0xf bound_ctrl:1
	v_add_f32_e32 v124, v78, v79
	v_add_f32_e32 v124, v124, v126
	v_mul_f32_e32 v125, 0.5, v81
	v_pk_mul_f32 v[50:51], v[120:121], v[50:51]
	v_add_f32_dpp v124, v124, v124 quad_perm:[1,0,3,2] row_mask:0xf bank_mask:0xf bound_ctrl:1
	v_pk_mul_f32 v[52:53], v[120:121], v[52:53]
	v_exp_f32_e32 v54, v54
	v_add_f32_dpp v152, v124, v124 quad_perm:[2,3,0,1] row_mask:0xf bank_mask:0xf bound_ctrl:1
	v_mov_b32_e32 v124, 0
	v_fma_f32 v126, 0.5, v53, v52
	v_exp_f32_e32 v55, v55
	v_mov_b32_dpp v124, v125 quad_perm:[1,0,3,2] row_mask:0xf bank_mask:0xf
	v_fmac_f32_e32 v124, 0.5, v81
	v_exp_f32_e32 v56, v56
	v_exp_f32_e32 v57, v57
	v_add_f32_dpp v153, v124, v124 quad_perm:[2,3,0,1] row_mask:0xf bank_mask:0xf bound_ctrl:1
	v_add_f32_e32 v124, v50, v51
	v_add_f32_e32 v124, v124, v126
	v_mul_f32_e32 v125, 0.5, v53
	v_pk_mul_f32 v[54:55], v[120:121], v[54:55]
	v_add_f32_dpp v124, v124, v124 quad_perm:[1,0,3,2] row_mask:0xf bank_mask:0xf bound_ctrl:1
	v_pk_mul_f32 v[56:57], v[120:121], v[56:57]
	v_exp_f32_e32 v58, v58
	v_add_f32_dpp v146, v124, v124 quad_perm:[2,3,0,1] row_mask:0xf bank_mask:0xf bound_ctrl:1
	v_mov_b32_e32 v124, 0
	v_fma_f32 v126, 0.5, v57, v56
	v_exp_f32_e32 v59, v59
	v_mov_b32_dpp v124, v125 quad_perm:[1,0,3,2] row_mask:0xf bank_mask:0xf
	v_fmac_f32_e32 v124, 0.5, v53
	v_exp_f32_e32 v60, v60
	v_exp_f32_e32 v61, v61
	v_add_f32_dpp v147, v124, v124 quad_perm:[2,3,0,1] row_mask:0xf bank_mask:0xf bound_ctrl:1
	v_add_f32_e32 v124, v54, v55
	v_add_f32_e32 v124, v124, v126
	v_mul_f32_e32 v125, 0.5, v57
	v_pk_mul_f32 v[58:59], v[120:121], v[58:59]
	v_add_f32_dpp v124, v124, v124 quad_perm:[1,0,3,2] row_mask:0xf bank_mask:0xf bound_ctrl:1
	v_pk_mul_f32 v[60:61], v[120:121], v[60:61]
	v_exp_f32_e32 v62, v62
	v_add_f32_dpp v144, v124, v124 quad_perm:[2,3,0,1] row_mask:0xf bank_mask:0xf bound_ctrl:1
	v_mov_b32_e32 v124, 0
	v_fma_f32 v126, 0.5, v61, v60
	v_exp_f32_e32 v63, v63
	v_mov_b32_dpp v124, v125 quad_perm:[1,0,3,2] row_mask:0xf bank_mask:0xf
	v_fmac_f32_e32 v124, 0.5, v57
	v_exp_f32_e32 v64, v64
	v_exp_f32_e32 v65, v65
	v_add_f32_dpp v145, v124, v124 quad_perm:[2,3,0,1] row_mask:0xf bank_mask:0xf bound_ctrl:1
	v_add_f32_e32 v124, v58, v59
	v_add_f32_e32 v124, v124, v126
	v_mul_f32_e32 v125, 0.5, v61
	v_pk_mul_f32 v[62:63], v[120:121], v[62:63]
	v_add_f32_dpp v124, v124, v124 quad_perm:[1,0,3,2] row_mask:0xf bank_mask:0xf bound_ctrl:1
	v_pk_mul_f32 v[64:65], v[120:121], v[64:65]
	v_mov_b32_e32 v219, v158
	v_add_f32_dpp v126, v124, v124 quad_perm:[2,3,0,1] row_mask:0xf bank_mask:0xf bound_ctrl:1
	v_mov_b32_e32 v124, 0
	v_fma_f32 v148, 0.5, v65, v64
	v_mov_b32_e32 v178, v159
	v_mov_b32_dpp v124, v125 quad_perm:[1,0,3,2] row_mask:0xf bank_mask:0xf
	v_fmac_f32_e32 v124, 0.5, v61
	v_mul_f32_e32 v125, 0.5, v65
	v_mov_b32_e32 v179, v170
	v_add_f32_dpp v127, v124, v124 quad_perm:[2,3,0,1] row_mask:0xf bank_mask:0xf bound_ctrl:1
	v_add_f32_e32 v124, v62, v63
	v_add_f32_e32 v124, v124, v148
	v_mov_b32_e32 v148, 0
	v_mov_b32_e32 v176, v171
	v_add_f32_dpp v124, v124, v124 quad_perm:[1,0,3,2] row_mask:0xf bank_mask:0xf bound_ctrl:1
	v_mov_b32_dpp v148, v125 quad_perm:[1,0,3,2] row_mask:0xf bank_mask:0xf
	v_fmac_f32_e32 v148, 0.5, v65
	v_add_f32_dpp v124, v124, v124 quad_perm:[2,3,0,1] row_mask:0xf bank_mask:0xf bound_ctrl:1
	v_mov_b32_e32 v177, v156
	v_add_f32_dpp v125, v148, v148 quad_perm:[2,3,0,1] row_mask:0xf bank_mask:0xf bound_ctrl:1
	v_mov_b32_e32 v174, v157
	v_mov_b32_e32 v175, v152
	v_mov_b32_e32 v172, v153
	v_mov_b32_e32 v173, v146
	v_mov_b32_e32 v154, v147
	v_mov_b32_e32 v155, v144
	v_mov_b32_e32 v150, v145
	v_mov_b32_e32 v151, v126
	v_mov_b32_e32 v148, v127
	v_mov_b32_e32 v149, v124
	v_mov_b32_e32 v218, v125
	v_permlane32_swap_b32_e32 v158, v219
	v_permlane32_swap_b32_e32 v159, v178
	v_permlane32_swap_b32_e32 v170, v179
	v_permlane32_swap_b32_e32 v171, v176
	v_permlane32_swap_b32_e32 v156, v177
	v_permlane32_swap_b32_e32 v157, v174
	v_permlane32_swap_b32_e32 v152, v175
	v_permlane32_swap_b32_e32 v153, v172
	v_permlane32_swap_b32_e32 v146, v173
	v_permlane32_swap_b32_e32 v147, v154
	v_permlane32_swap_b32_e32 v144, v155
	v_permlane32_swap_b32_e32 v145, v150
	v_permlane32_swap_b32_e32 v126, v151
	v_permlane32_swap_b32_e32 v127, v148
	v_permlane32_swap_b32_e32 v124, v149
	v_permlane32_swap_b32_e32 v125, v218
	s_and_saveexec_b64 s[10:11], s[6:7]
	s_cbranch_execz .LBB0_868
	ds_read2_b32 v[220:221], v0 offset1:1
	v_add_f32_e32 v159, v219, v159
	v_add_f32_e32 v156, v176, v156
	v_add_f32_e32 v157, v177, v157
	v_add_f32_e32 v152, v174, v152
	v_add_f32_e32 v153, v175, v153
	v_add_f32_e32 v146, v172, v146
	v_add_f32_e32 v147, v173, v147
	s_waitcnt lgkmcnt(0)
	v_add_f32_e32 v158, v220, v158
	v_add_f32_e32 v159, v221, v159
	ds_write2_b32 v0, v158, v159 offset1:1
	v_add_f32_e32 v158, v178, v170
	v_add_f32_e32 v159, v179, v171
	ds_read2_b32 v[170:171], v0 offset0:2 offset1:3
	v_add_f32_e32 v144, v154, v144
	v_add_f32_e32 v145, v155, v145
	v_add_f32_e32 v126, v150, v126
	v_add_f32_e32 v127, v151, v127
	v_add_f32_e32 v124, v148, v124
	v_add_f32_e32 v125, v149, v125
	s_waitcnt lgkmcnt(0)
	v_add_f32_e32 v158, v158, v170
	v_add_f32_e32 v159, v159, v171
	ds_write2_b32 v0, v158, v159 offset0:2 offset1:3
	ds_read2_b32 v[158:159], v0 offset0:4 offset1:5
	s_waitcnt lgkmcnt(0)
	v_add_f32_e32 v156, v156, v158
	v_add_f32_e32 v157, v157, v159
	ds_write2_b32 v0, v156, v157 offset0:4 offset1:5
	ds_read2_b32 v[156:157], v0 offset0:6 offset1:7
	s_waitcnt lgkmcnt(0)
	v_add_f32_e32 v152, v152, v156
	v_add_f32_e32 v153, v153, v157
	ds_write2_b32 v0, v152, v153 offset0:6 offset1:7
	ds_read2_b32 v[152:153], v0 offset0:8 offset1:9
	s_waitcnt lgkmcnt(0)
	v_add_f32_e32 v146, v146, v152
	v_add_f32_e32 v147, v147, v153
	ds_write2_b32 v0, v146, v147 offset0:8 offset1:9
	ds_read2_b32 v[146:147], v0 offset0:10 offset1:11
	s_waitcnt lgkmcnt(0)
	v_add_f32_e32 v144, v144, v146
	v_add_f32_e32 v145, v145, v147
	ds_write2_b32 v0, v144, v145 offset0:10 offset1:11
	ds_read2_b32 v[144:145], v0 offset0:12 offset1:13
	s_waitcnt lgkmcnt(0)
	v_add_f32_e32 v126, v126, v144
	v_add_f32_e32 v127, v127, v145
	ds_write2_b32 v0, v126, v127 offset0:12 offset1:13
	ds_read2_b32 v[126:127], v0 offset0:14 offset1:15
	s_waitcnt lgkmcnt(0)
	v_add_f32_e32 v124, v124, v126
	v_add_f32_e32 v125, v125, v127
	ds_write2_b32 v0, v124, v125 offset0:14 offset1:15
	ds_read_b32 v124, v0 offset:64
	s_waitcnt lgkmcnt(0)
	v_add_f32_e32 v124, v124, v218
	ds_write_b32 v0, v124 offset:64

.LBB0_875:
	s_nop 7
	v_exp_f32_e32 v18, v18
	v_exp_f32_e32 v19, v19
	v_exp_f32_e32 v20, v20
	v_exp_f32_e32 v21, v21
	v_exp_f32_e32 v22, v22
	v_pk_mul_f32 v[18:19], v[120:121], v[18:19]
	v_exp_f32_e32 v23, v23
	v_pk_mul_f32 v[20:21], v[120:121], v[20:21]
	v_add_f32_e32 v124, v18, v19
	v_fma_f32 v126, 0.5, v21, v20
	v_exp_f32_e32 v24, v24
	v_exp_f32_e32 v25, v25
	v_add_f32_e32 v124, v124, v126
	v_mul_f32_e32 v125, 0.5, v21
	v_pk_mul_f32 v[22:23], v[120:121], v[22:23]
	v_add_f32_dpp v124, v124, v124 quad_perm:[1,0,3,2] row_mask:0xf bank_mask:0xf bound_ctrl:1
	v_pk_mul_f32 v[24:25], v[120:121], v[24:25]
	v_exp_f32_e32 v26, v26
	v_add_f32_dpp v158, v124, v124 quad_perm:[2,3,0,1] row_mask:0xf bank_mask:0xf bound_ctrl:1
	v_mov_b32_e32 v124, 0
	v_fma_f32 v126, 0.5, v25, v24
	v_exp_f32_e32 v27, v27
	v_mov_b32_dpp v124, v125 quad_perm:[1,0,3,2] row_mask:0xf bank_mask:0xf
	v_fmac_f32_e32 v124, 0.5, v21
	v_exp_f32_e32 v28, v28
	v_exp_f32_e32 v29, v29
	v_add_f32_dpp v159, v124, v124 quad_perm:[2,3,0,1] row_mask:0xf bank_mask:0xf bound_ctrl:1
	v_add_f32_e32 v124, v22, v23
	v_add_f32_e32 v124, v124, v126
	v_mul_f32_e32 v125, 0.5, v25
	v_pk_mul_f32 v[26:27], v[120:121], v[26:27]
	v_add_f32_dpp v124, v124, v124 quad_perm:[1,0,3,2] row_mask:0xf bank_mask:0xf bound_ctrl:1
	v_pk_mul_f32 v[28:29], v[120:121], v[28:29]
	v_exp_f32_e32 v30, v30
	v_add_f32_dpp v170, v124, v124 quad_perm:[2,3,0,1] row_mask:0xf bank_mask:0xf bound_ctrl:1
	v_mov_b32_e32 v124, 0
	v_fma_f32 v126, 0.5, v29, v28
	v_exp_f32_e32 v31, v31
	v_mov_b32_dpp v124, v125 quad_perm:[1,0,3,2] row_mask:0xf bank_mask:0xf
	v_fmac_f32_e32 v124, 0.5, v25
	v_exp_f32_e32 v32, v32
	v_exp_f32_e32 v33, v33
	v_add_f32_dpp v171, v124, v124 quad_perm:[2,3,0,1] row_mask:0xf bank_mask:0xf bound_ctrl:1
	v_add_f32_e32 v124, v26, v27
	v_add_f32_e32 v124, v124, v126
	v_mul_f32_e32 v125, 0.5, v29
	v_pk_mul_f32 v[30:31], v[120:121], v[30:31]
	v_add_f32_dpp v124, v124, v124 quad_perm:[1,0,3,2] row_mask:0xf bank_mask:0xf bound_ctrl:1
	v_pk_mul_f32 v[32:33], v[120:121], v[32:33]
	v_exp_f32_e32 v2, v2
	v_add_f32_dpp v156, v124, v124 quad_perm:[2,3,0,1] row_mask:0xf bank_mask:0xf bound_ctrl:1
	v_mov_b32_e32 v124, 0
	v_fma_f32 v126, 0.5, v33, v32
	v_exp_f32_e32 v3, v3
	v_mov_b32_dpp v124, v125 quad_perm:[1,0,3,2] row_mask:0xf bank_mask:0xf
	v_fmac_f32_e32 v124, 0.5, v29
	v_exp_f32_e32 v4, v4
	v_exp_f32_e32 v5, v5
	v_add_f32_dpp v157, v124, v124 quad_perm:[2,3,0,1] row_mask:0xf bank_mask:0xf bound_ctrl:1
	v_add_f32_e32 v124, v30, v31
	v_add_f32_e32 v124, v124, v126
	v_mul_f32_e32 v125, 0.5, v33
	v_pk_mul_f32 v[2:3], v[120:121], v[2:3]
	v_add_f32_dpp v124, v124, v124 quad_perm:[1,0,3,2] row_mask:0xf bank_mask:0xf bound_ctrl:1
	v_pk_mul_f32 v[4:5], v[120:121], v[4:5]
	v_exp_f32_e32 v6, v6
	v_add_f32_dpp v152, v124, v124 quad_perm:[2,3,0,1] row_mask:0xf bank_mask:0xf bound_ctrl:1
	v_mov_b32_e32 v124, 0
	v_fma_f32 v126, 0.5, v5, v4
	v_exp_f32_e32 v7, v7
	v_mov_b32_dpp v124, v125 quad_perm:[1,0,3,2] row_mask:0xf bank_mask:0xf
	v_fmac_f32_e32 v124, 0.5, v33
	v_exp_f32_e32 v8, v8
	v_exp_f32_e32 v9, v9
	v_add_f32_dpp v153, v124, v124 quad_perm:[2,3,0,1] row_mask:0xf bank_mask:0xf bound_ctrl:1
	v_add_f32_e32 v124, v2, v3
	v_add_f32_e32 v124, v124, v126
	v_mul_f32_e32 v125, 0.5, v5
	v_pk_mul_f32 v[6:7], v[120:121], v[6:7]
	v_add_f32_dpp v124, v124, v124 quad_perm:[1,0,3,2] row_mask:0xf bank_mask:0xf bound_ctrl:1
	v_pk_mul_f32 v[8:9], v[120:121], v[8:9]
	v_exp_f32_e32 v10, v10
	v_add_f32_dpp v146, v124, v124 quad_perm:[2,3,0,1] row_mask:0xf bank_mask:0xf bound_ctrl:1
	v_mov_b32_e32 v124, 0
	v_fma_f32 v126, 0.5, v9, v8
	v_exp_f32_e32 v11, v11
	v_mov_b32_dpp v124, v125 quad_perm:[1,0,3,2] row_mask:0xf bank_mask:0xf
	v_fmac_f32_e32 v124, 0.5, v5
	v_exp_f32_e32 v12, v12
	v_exp_f32_e32 v13, v13
	v_add_f32_dpp v147, v124, v124 quad_perm:[2,3,0,1] row_mask:0xf bank_mask:0xf bound_ctrl:1
	v_add_f32_e32 v124, v6, v7
	v_add_f32_e32 v124, v124, v126
	v_mul_f32_e32 v125, 0.5, v9
	v_pk_mul_f32 v[10:11], v[120:121], v[10:11]
	v_add_f32_dpp v124, v124, v124 quad_perm:[1,0,3,2] row_mask:0xf bank_mask:0xf bound_ctrl:1
	v_pk_mul_f32 v[12:13], v[120:121], v[12:13]
	v_exp_f32_e32 v14, v14
	v_add_f32_dpp v144, v124, v124 quad_perm:[2,3,0,1] row_mask:0xf bank_mask:0xf bound_ctrl:1
	v_mov_b32_e32 v124, 0
	v_fma_f32 v126, 0.5, v13, v12
	v_exp_f32_e32 v15, v15
	v_mov_b32_dpp v124, v125 quad_perm:[1,0,3,2] row_mask:0xf bank_mask:0xf
	v_fmac_f32_e32 v124, 0.5, v9
	v_exp_f32_e32 v16, v16
	v_exp_f32_e32 v17, v17
	v_add_f32_dpp v145, v124, v124 quad_perm:[2,3,0,1] row_mask:0xf bank_mask:0xf bound_ctrl:1
	v_add_f32_e32 v124, v10, v11
	v_add_f32_e32 v124, v124, v126
	v_mul_f32_e32 v125, 0.5, v13
	v_pk_mul_f32 v[14:15], v[120:121], v[14:15]
	v_add_f32_dpp v124, v124, v124 quad_perm:[1,0,3,2] row_mask:0xf bank_mask:0xf bound_ctrl:1
	v_pk_mul_f32 v[16:17], v[120:121], v[16:17]
	v_mov_b32_e32 v219, v158
	v_add_f32_dpp v126, v124, v124 quad_perm:[2,3,0,1] row_mask:0xf bank_mask:0xf bound_ctrl:1
	v_mov_b32_e32 v124, 0
	v_fma_f32 v148, 0.5, v17, v16
	v_mov_b32_e32 v178, v159
	v_mov_b32_dpp v124, v125 quad_perm:[1,0,3,2] row_mask:0xf bank_mask:0xf
	v_fmac_f32_e32 v124, 0.5, v13
	v_mul_f32_e32 v125, 0.5, v17
	v_mov_b32_e32 v179, v170
	v_add_f32_dpp v127, v124, v124 quad_perm:[2,3,0,1] row_mask:0xf bank_mask:0xf bound_ctrl:1
	v_add_f32_e32 v124, v14, v15
	v_add_f32_e32 v124, v124, v148
	v_mov_b32_e32 v148, 0
	v_mov_b32_e32 v176, v171
	v_add_f32_dpp v124, v124, v124 quad_perm:[1,0,3,2] row_mask:0xf bank_mask:0xf bound_ctrl:1
	v_mov_b32_dpp v148, v125 quad_perm:[1,0,3,2] row_mask:0xf bank_mask:0xf
	v_fmac_f32_e32 v148, 0.5, v17
	v_add_f32_dpp v124, v124, v124 quad_perm:[2,3,0,1] row_mask:0xf bank_mask:0xf bound_ctrl:1
	v_mov_b32_e32 v177, v156
	v_add_f32_dpp v125, v148, v148 quad_perm:[2,3,0,1] row_mask:0xf bank_mask:0xf bound_ctrl:1
	v_mov_b32_e32 v174, v157
	v_mov_b32_e32 v175, v152
	v_mov_b32_e32 v172, v153
	v_mov_b32_e32 v173, v146
	v_mov_b32_e32 v154, v147
	v_mov_b32_e32 v155, v144
	v_mov_b32_e32 v150, v145
	v_mov_b32_e32 v151, v126
	v_mov_b32_e32 v148, v127
	v_mov_b32_e32 v149, v124
	v_mov_b32_e32 v218, v125
	v_permlane32_swap_b32_e32 v158, v219
	v_permlane32_swap_b32_e32 v159, v178
	v_permlane32_swap_b32_e32 v170, v179
	v_permlane32_swap_b32_e32 v171, v176
	v_permlane32_swap_b32_e32 v156, v177
	v_permlane32_swap_b32_e32 v157, v174
	v_permlane32_swap_b32_e32 v152, v175
	v_permlane32_swap_b32_e32 v153, v172
	v_permlane32_swap_b32_e32 v146, v173
	v_permlane32_swap_b32_e32 v147, v154
	v_permlane32_swap_b32_e32 v144, v155
	v_permlane32_swap_b32_e32 v145, v150
	v_permlane32_swap_b32_e32 v126, v151
	v_permlane32_swap_b32_e32 v127, v148
	v_permlane32_swap_b32_e32 v124, v149
	v_permlane32_swap_b32_e32 v125, v218
	s_and_saveexec_b64 s[10:11], s[6:7]
	s_cbranch_execz .LBB0_877
	ds_read2_b32 v[220:221], v0 offset0:16 offset1:17
	v_add_f32_e32 v159, v219, v159
	v_add_f32_e32 v156, v176, v156
	v_add_f32_e32 v157, v177, v157
	v_add_f32_e32 v152, v174, v152
	v_add_f32_e32 v153, v175, v153
	v_add_f32_e32 v146, v172, v146
	v_add_f32_e32 v147, v173, v147
	s_waitcnt lgkmcnt(0)
	v_add_f32_e32 v158, v220, v158
	v_add_f32_e32 v159, v221, v159
	ds_write2_b32 v0, v158, v159 offset0:16 offset1:17
	v_add_f32_e32 v158, v178, v170
	v_add_f32_e32 v159, v179, v171
	ds_read2_b32 v[170:171], v0 offset0:18 offset1:19
	v_add_f32_e32 v144, v154, v144
	v_add_f32_e32 v145, v155, v145
	v_add_f32_e32 v126, v150, v126
	v_add_f32_e32 v127, v151, v127
	v_add_f32_e32 v124, v148, v124
	v_add_f32_e32 v125, v149, v125
	s_waitcnt lgkmcnt(0)
	v_add_f32_e32 v158, v158, v170
	v_add_f32_e32 v159, v159, v171
	ds_write2_b32 v0, v158, v159 offset0:18 offset1:19
	ds_read2_b32 v[158:159], v0 offset0:20 offset1:21
	s_waitcnt lgkmcnt(0)
	v_add_f32_e32 v156, v156, v158
	v_add_f32_e32 v157, v157, v159
	ds_write2_b32 v0, v156, v157 offset0:20 offset1:21
	ds_read2_b32 v[156:157], v0 offset0:22 offset1:23
	s_waitcnt lgkmcnt(0)
	v_add_f32_e32 v152, v152, v156
	v_add_f32_e32 v153, v153, v157
	ds_write2_b32 v0, v152, v153 offset0:22 offset1:23
	ds_read2_b32 v[152:153], v0 offset0:24 offset1:25
	s_waitcnt lgkmcnt(0)
	v_add_f32_e32 v146, v146, v152
	v_add_f32_e32 v147, v147, v153
	ds_write2_b32 v0, v146, v147 offset0:24 offset1:25
	ds_read2_b32 v[146:147], v0 offset0:26 offset1:27
	s_waitcnt lgkmcnt(0)
	v_add_f32_e32 v144, v144, v146
	v_add_f32_e32 v145, v145, v147
	ds_write2_b32 v0, v144, v145 offset0:26 offset1:27
	ds_read2_b32 v[144:145], v0 offset0:28 offset1:29
	s_waitcnt lgkmcnt(0)
	v_add_f32_e32 v126, v126, v144
	v_add_f32_e32 v127, v127, v145
	ds_write2_b32 v0, v126, v127 offset0:28 offset1:29
	ds_read2_b32 v[126:127], v0 offset0:30 offset1:31
	s_waitcnt lgkmcnt(0)
	v_add_f32_e32 v124, v124, v126
	v_add_f32_e32 v125, v125, v127
	ds_write2_b32 v0, v124, v125 offset0:30 offset1:31
	ds_read_b32 v124, v0 offset:128
	s_waitcnt lgkmcnt(0)
	v_add_f32_e32 v124, v124, v218
	ds_write_b32 v0, v124 offset:128

.LBB0_995:
	v_exp_f32_e32 v4, v80
	v_exp_f32_e32 v5, v81
	v_exp_f32_e32 v12, v64
	v_exp_f32_e32 v13, v65
	v_exp_f32_e32 v6, v82
	v_exp_f32_e32 v7, v83
	v_exp_f32_e32 v14, v66
	v_exp_f32_e32 v15, v67
	v_add_f32_e32 v2, 0, v4
	v_add_f32_e32 v3, 0, v5
	v_exp_f32_e32 v8, v84
	v_exp_f32_e32 v9, v85
	v_add_f32_e32 v2, v12, v2
	v_add_f32_e32 v3, v13, v3
	v_exp_f32_e32 v64, v68
	v_exp_f32_e32 v65, v69
	v_add_f32_e32 v2, v6, v2
	v_add_f32_e32 v3, v7, v3
	v_exp_f32_e32 v10, v86
	v_exp_f32_e32 v11, v87
	v_add_f32_e32 v2, v14, v2
	v_add_f32_e32 v3, v15, v3
	v_exp_f32_e32 v66, v70
	v_exp_f32_e32 v67, v71
	v_add_f32_e32 v2, v8, v2
	v_add_f32_e32 v3, v9, v3
	v_exp_f32_e32 v68, v88
	v_exp_f32_e32 v69, v89
	v_add_f32_e32 v2, v64, v2
	v_add_f32_e32 v3, v65, v3
	v_exp_f32_e32 v70, v72
	v_exp_f32_e32 v71, v73
	v_add_f32_e32 v2, v10, v2
	v_add_f32_e32 v3, v11, v3
	v_exp_f32_e32 v72, v90
	v_exp_f32_e32 v73, v91
	v_add_f32_e32 v2, v66, v2
	v_add_f32_e32 v3, v67, v3
	v_exp_f32_e32 v74, v74
	v_exp_f32_e32 v75, v75
	v_add_f32_e32 v2, v68, v2
	v_add_f32_e32 v3, v69, v3
	v_exp_f32_e32 v80, v92
	v_exp_f32_e32 v81, v93
	v_add_f32_e32 v2, v70, v2
	v_add_f32_e32 v3, v71, v3
	v_exp_f32_e32 v76, v76
	v_exp_f32_e32 v77, v77
	v_add_f32_e32 v2, v72, v2
	v_add_f32_e32 v3, v73, v3
	v_exp_f32_e32 v82, v94
	v_exp_f32_e32 v83, v95
	v_add_f32_e32 v2, v74, v2
	v_add_f32_e32 v3, v75, v3
	v_exp_f32_e32 v78, v78
	v_exp_f32_e32 v79, v79
	v_add_f32_e32 v2, v80, v2
	v_add_f32_e32 v3, v81, v3
	v_cvt_pk_bf16_f32 v4, v4, v5
	v_add_f32_e32 v2, v76, v2
	v_add_f32_e32 v3, v77, v3
	v_cvt_pk_bf16_f32 v5, v6, v7
	v_add_f32_e32 v2, v82, v2
	v_add_f32_e32 v3, v83, v3
	v_cvt_pk_bf16_f32 v6, v8, v9
	v_add_f32_e32 v2, v78, v2
	v_add_f32_e32 v3, v79, v3
	v_cvt_pk_bf16_f32 v8, v68, v69
	v_cvt_pk_bf16_f32 v9, v72, v73
	v_cvt_pk_bf16_f32 v12, v12, v13
	v_cvt_pk_bf16_f32 v13, v14, v15
	v_cvt_pk_bf16_f32 v14, v64, v65
	v_cvt_pk_bf16_f32 v15, v66, v67
	v_cvt_pk_bf16_f32 v98, v70, v71
	v_cvt_pk_bf16_f32 v99, v74, v75
	v_cvt_pk_bf16_f32 v100, v76, v77
	v_cvt_pk_bf16_f32 v101, v78, v79
	ds_read_b128 v[64:67], v0 offset:9216
	ds_read_b128 v[68:71], v0 offset:9248
	ds_read_b128 v[72:75], v0 offset:9280
	ds_read_b128 v[76:79], v0 offset:9312
	s_add_i32 s0, s9, 1
	s_cmp_lg_u32 s0, 3
	s_cselect_b32 s14, s0, 0
	s_add_i32 s0, s14, 1
	v_pk_add_f32 v[2:3], v[2:3], v[2:3] op_sel:[0,1] op_sel_hi:[1,0]
	s_cmp_lg_u32 s0, 3
	v_mov_b32_e32 v3, v2
	s_cselect_b32 s9, s0, 0
	s_nop 0
	v_permlane32_swap_b32_e32 v2, v3
	v_cvt_pk_bf16_f32 v7, v10, v11
	v_cvt_pk_bf16_f32 v10, v80, v81
	v_cvt_pk_bf16_f32 v11, v82, v83
	s_waitcnt lgkmcnt(3)
	v_mfma_f32_32x32x16_bf16 v[16:31], v[64:67], v[4:7], v[16:31]
	s_waitcnt lgkmcnt(2)
	v_mfma_f32_32x32x16_bf16 v[16:31], v[68:71], v[8:11], v[16:31]
	s_waitcnt lgkmcnt(1)
	v_mfma_f32_32x32x16_bf16 v[16:31], v[72:75], v[12:15], v[16:31]
	s_waitcnt lgkmcnt(0)
	v_mfma_f32_32x32x16_bf16 v[80:95], v[76:79], v[98:101], v[16:31]
	s_nop 7
	ds_read_b128 v[16:19], v0 offset:13824
	ds_read_b128 v[20:23], v0 offset:13856
	ds_read_b128 v[24:27], v0 offset:13888
	ds_read_b128 v[28:31], v0 offset:13920
	s_waitcnt lgkmcnt(3)
	v_mfma_f32_32x32x16_bf16 v[48:63], v[16:19], v[4:7], v[48:63]
	s_waitcnt lgkmcnt(2)
	v_mfma_f32_32x32x16_bf16 v[48:63], v[20:23], v[8:11], v[48:63]
	s_waitcnt lgkmcnt(1)
	v_mfma_f32_32x32x16_bf16 v[48:63], v[24:27], v[12:15], v[48:63]
	s_waitcnt lgkmcnt(0)
	v_mfma_f32_32x32x16_bf16 v[64:79], v[28:31], v[98:101], v[48:63]
	s_add_i32 s12, s10, -2
	s_cmp_gt_i32 s12, s6
	s_cbranch_scc1 .LBB0_997
	s_mul_i32 s0, s9, 0x4900
	v_add_u32_e32 v0, s0, v171
	s_waitcnt vmcnt(1)
	ds_write_b128 v0, v[144:147]
	s_waitcnt vmcnt(0)
	ds_write_b128 v0, v[148:151] offset:9216

.LBB0_1005:
	v_exp_f32_e32 v6, v112
	v_exp_f32_e32 v7, v113
	v_exp_f32_e32 v14, v96
	v_exp_f32_e32 v15, v97
	v_exp_f32_e32 v8, v114
	v_exp_f32_e32 v9, v115
	v_exp_f32_e32 v98, v98
	v_exp_f32_e32 v99, v99
	v_add_f32_e32 v2, 0, v6
	v_add_f32_e32 v3, 0, v7
	v_exp_f32_e32 v10, v116
	v_exp_f32_e32 v11, v117
	v_add_f32_e32 v2, v14, v2
	v_add_f32_e32 v3, v15, v3
	v_exp_f32_e32 v100, v100
	v_exp_f32_e32 v101, v101
	v_add_f32_e32 v2, v8, v2
	v_add_f32_e32 v3, v9, v3
	v_exp_f32_e32 v12, v118
	v_exp_f32_e32 v13, v119
	v_add_f32_e32 v2, v98, v2
	v_add_f32_e32 v3, v99, v3
	v_exp_f32_e32 v102, v102
	v_exp_f32_e32 v103, v103
	v_add_f32_e32 v2, v10, v2
	v_add_f32_e32 v3, v11, v3
	v_exp_f32_e32 v96, v120
	v_exp_f32_e32 v97, v121
	v_add_f32_e32 v2, v100, v2
	v_add_f32_e32 v3, v101, v3
	v_exp_f32_e32 v104, v104
	v_exp_f32_e32 v105, v105
	v_add_f32_e32 v2, v12, v2
	v_add_f32_e32 v3, v13, v3
	v_exp_f32_e32 v112, v122
	v_exp_f32_e32 v113, v123
	v_add_f32_e32 v2, v102, v2
	v_add_f32_e32 v3, v103, v3
	v_exp_f32_e32 v106, v106
	v_exp_f32_e32 v107, v107
	v_add_f32_e32 v2, v96, v2
	v_add_f32_e32 v3, v97, v3
	v_exp_f32_e32 v114, v124
	v_exp_f32_e32 v115, v125
	v_add_f32_e32 v2, v104, v2
	v_add_f32_e32 v3, v105, v3
	v_exp_f32_e32 v108, v108
	v_exp_f32_e32 v109, v109
	v_add_f32_e32 v2, v112, v2
	v_add_f32_e32 v3, v113, v3
	v_exp_f32_e32 v116, v126
	v_exp_f32_e32 v117, v127
	v_add_f32_e32 v2, v106, v2
	v_add_f32_e32 v3, v107, v3
	v_exp_f32_e32 v110, v110
	v_exp_f32_e32 v111, v111
	v_add_f32_e32 v2, v114, v2
	v_add_f32_e32 v3, v115, v3
	v_cvt_pk_bf16_f32 v6, v6, v7
	v_add_f32_e32 v2, v108, v2
	v_add_f32_e32 v3, v109, v3
	v_cvt_pk_bf16_f32 v7, v8, v9
	v_add_f32_e32 v2, v116, v2
	v_add_f32_e32 v3, v117, v3
	v_cvt_pk_bf16_f32 v8, v10, v11
	v_add_f32_e32 v2, v110, v2
	v_add_f32_e32 v3, v111, v3
	v_cvt_pk_bf16_f32 v9, v12, v13
	v_cvt_pk_bf16_f32 v10, v96, v97
	v_cvt_pk_bf16_f32 v11, v112, v113
	v_cvt_pk_bf16_f32 v12, v114, v115
	v_cvt_pk_bf16_f32 v13, v116, v117
	v_cvt_pk_bf16_f32 v97, v98, v99
	v_cvt_pk_bf16_f32 v98, v100, v101
	v_cvt_pk_bf16_f32 v99, v102, v103
	v_cvt_pk_bf16_f32 v100, v104, v105
	v_cvt_pk_bf16_f32 v101, v106, v107
	v_cvt_pk_bf16_f32 v102, v108, v109
	v_cvt_pk_bf16_f32 v103, v110, v111
	ds_read_b128 v[104:107], v4 offset:9216
	ds_read_b128 v[108:111], v4 offset:9248
	ds_read_b128 v[112:115], v4 offset:9280
	ds_read_b128 v[116:119], v4 offset:9312
	v_pk_add_f32 v[2:3], v[2:3], v[2:3] op_sel:[0,1] op_sel_hi:[1,0]
	v_cvt_pk_bf16_f32 v96, v14, v15
	v_mov_b32_e32 v3, v2
	s_nop 1
	v_permlane32_swap_b32_e32 v2, v3
	s_waitcnt lgkmcnt(3)
	v_mfma_f32_32x32x16_bf16 v[16:31], v[104:107], v[6:9], v[80:95]
	s_waitcnt lgkmcnt(2)
	v_mfma_f32_32x32x16_bf16 v[16:31], v[108:111], v[10:13], v[16:31]
	s_waitcnt lgkmcnt(1)
	v_mfma_f32_32x32x16_bf16 v[16:31], v[112:115], v[96:99], v[16:31]
	s_waitcnt lgkmcnt(0)
	v_mfma_f32_32x32x16_bf16 v[16:31], v[116:119], v[100:103], v[16:31]
	ds_read_b128 v[104:107], v4 offset:13824
	ds_read_b128 v[108:111], v4 offset:13856
	ds_read_b128 v[112:115], v4 offset:13888
	ds_read_b128 v[116:119], v4 offset:13920
	s_waitcnt lgkmcnt(3)
	v_mfma_f32_32x32x16_bf16 v[48:63], v[104:107], v[6:9], v[64:79]
	s_waitcnt lgkmcnt(2)
	v_mfma_f32_32x32x16_bf16 v[48:63], v[108:111], v[10:13], v[48:63]
	s_waitcnt lgkmcnt(1)
	v_mfma_f32_32x32x16_bf16 v[48:63], v[112:115], v[96:99], v[48:63]
	s_waitcnt lgkmcnt(0)
	v_mfma_f32_32x32x16_bf16 v[48:63], v[116:119], v[100:103], v[48:63]
	s_andn2_b64 vcc, exec, s[2:3]
	s_cbranch_vccnz .LBB0_1007
	v_add3_u32 v4, s11, v207, v170
	s_waitcnt vmcnt(1)
	ds_write_b128 v4, v[152:155]
	s_waitcnt vmcnt(0)
	ds_write_b128 v4, v[156:159] offset:9216
